# attention tile loop instruction diet: no per-tile NM copies, single vmcnt wait, scalar-compare flags, LDS-DMA via SGPR-base addressing (25 fewer instructions per wave-tile)
# speedup vs baseline: 1.0146x; 1.0131x over previous
.LBB0_1124:
	v_cvt_pk_bf16_f32 v64, v83, v147
	v_cvt_pk_bf16_f32 v65, v149, v151
	v_cvt_pk_bf16_f32 v66, v153, v155
	v_cvt_pk_bf16_f32 v67, v157, v159
	s_lshl_b32 s8, s0, 7
	s_add_i32 s0, s90, s8
	s_waitcnt lgkmcnt(0)
	v_mfma_f32_32x32x16_bf16 v[48:63], v[112:115], v[64:67], v[48:63]
	s_mov_b32 s1, s53
	v_lshl_add_u64 v[68:69], v[196:197], 0, s[0:1]
	v_mad_u64_u32 v[70:71], s[0:1], v68, s96, 0
	s_waitcnt vmcnt(6)
	v_mad_i32_i24 v203, v69, s96, v71
	v_or_b32_e32 v202, v194, v70
	v_mfma_f32_32x32x16_bf16 v[32:47], v[116:119], v[64:67], v[32:47]
	s_waitcnt lgkmcnt(0)
	s_barrier
	s_add_i32 s0, s83, s8
	s_mov_b32 s1, s53
	s_mov_b32 s37, 1
	v_lshl_add_u64 v[204:205], s[0:1], 1, v[198:199]
	v_mov_b32_e32 v82, v81
	v_mfma_f32_32x32x16_bf16 v[16:31], v[108:111], v[64:67], v[16:31]
	v_mov_b32_e32 v83, v81
	v_add_f32_e32 v177, v124, v125
	v_mfma_f32_32x32x16_bf16 v[0:15], v[104:107], v[64:67], v[0:15]
	v_cvt_pk_bf16_f32 v64, v88, v94
	v_cvt_pk_bf16_f32 v65, v126, v144
	v_cvt_pk_bf16_f32 v66, v89, v95
	v_cvt_pk_bf16_f32 v67, v127, v145
	v_mov_b32_e32 v88, v81
	v_mov_b32_e32 v89, v81
	v_mov_b32_e32 v94, v81
	v_mfma_f32_32x32x16_bf16 v[48:63], v[84:87], v[64:67], v[48:63]
	v_mov_b32_e32 v84, v81
	v_mov_b32_e32 v85, v81
	v_mov_b32_e32 v86, v81
	v_mov_b32_e32 v87, v81
	v_mov_b32_e32 v95, v81
	v_mfma_f32_32x32x16_bf16 v[32:47], v[90:93], v[64:67], v[32:47]
	v_mov_b32_e32 v90, v81
	v_mov_b32_e32 v91, v81
	v_mov_b32_e32 v92, v81
	v_mov_b32_e32 v93, v81
	v_mfma_f32_32x32x16_bf16 v[16:31], v[100:103], v[64:67], v[16:31]
	ds_read_b128 v[68:71], v160 offset:32768
	ds_read_b128 v[72:75], v161 offset:32768
	ds_read_b128 v[76:79], v162 offset:32768
	ds_read_b128 v[100:103], v163 offset:32768
	v_mfma_f32_32x32x16_bf16 v[0:15], v[96:99], v[64:67], v[0:15]
	s_mov_b64 s[0:1], 0x88180
	v_lshl_add_u64 v[64:65], v[122:123], 0, s[0:1]
	s_mov_b64 s[0:1], 0xe0000
	v_lshl_add_u64 v[66:67], v[120:121], 0, s[0:1]
	s_mov_b32 m0, s33
	v_mov_b64_e32 v[126:127], v[94:95]
	global_load_lds_dwordx4 v[66:67], off
	s_mov_b32 m0, s38
	v_mov_b64_e32 v[124:125], v[92:93]
	global_load_lds_dwordx4 v[64:65], off
	v_mov_b64_e32 v[122:123], v[90:91]
	v_mov_b64_e32 v[120:121], v[88:89]
	v_mov_b64_e32 v[118:119], v[86:87]
	v_mov_b64_e32 v[116:117], v[84:85]
	v_mov_b64_e32 v[114:115], v[82:83]
	v_mov_b64_e32 v[112:113], v[80:81]
	s_mov_b32 s39, 0x20000
	v_mov_b32_e32 v80, v81
	s_waitcnt lgkmcnt(0)
	v_mfma_f32_32x32x16_bf16 v[112:127], v[68:71], v[128:131], v[112:127]
	v_mfma_f32_32x32x16_bf16 v[112:127], v[72:75], v[132:135], v[112:127]
	v_mfma_f32_32x32x16_bf16 v[112:127], v[76:79], v[136:139], v[112:127]
	v_mfma_f32_32x32x16_bf16 v[112:127], v[100:103], v[140:143], v[112:127]
	s_add_u32 s98, s28, 0xa600000
	s_addc_u32 s99, s29, 0
	s_add_u32 s100, s28, 0xe900200
	s_addc_u32 s101, s29, 0
	s_branch .LBB0_1126
.LBB0_1125:
	s_waitcnt lgkmcnt(0)
	v_mfma_f32_32x32x16_bf16 v[112:127], v[100:103], v[128:131], v[80:95]
	s_add_i32 s39, s39, 0x8000
	s_add_i32 s37, s37, 1
	v_add_f32_e32 v177, v169, v168
	v_lshl_add_u64 v[202:203], v[202:203], 0, s[84:85]
	v_lshl_add_u64 v[204:205], v[204:205], 0, s[72:73]
	s_cmp_eq_u32 s39, 0x228000
	v_mfma_f32_32x32x16_bf16 v[112:127], v[96:99], v[132:135], v[112:127]
	v_mfma_f32_32x32x16_bf16 v[112:127], v[104:107], v[136:139], v[112:127]
	v_mfma_f32_32x32x16_bf16 v[112:127], v[108:111], v[140:143], v[112:127]
	s_cbranch_scc1 .LBB0_1139
.LBB0_1126:
	s_add_i32 s0, s39, 0xfffe8000
	s_and_b32 s36, s0, 0x18000
	v_or_b32_e32 v250, s36, v238
	v_or_b32_e32 v72, s36, v195
	v_add_u32_e32 v64, v72, v234
	v_add_u32_e32 v68, v72, v235
	v_add_u32_e32 v73, v72, v236
	v_add_u32_e32 v76, v72, v237
	v_add_u32_e32 v96, v250, v239
	ds_read_b128 v[64:67], v64 offset:8192
	ds_read_b128 v[68:71], v68 offset:8192
	ds_read_b128 v[72:75], v73 offset:8192
	ds_read_b128 v[76:79], v76 offset:8192
	ds_read_b128 v[172:175], v96 offset:16384
	ds_read_b128 v[144:147], v96 offset:20480
	ds_read_b128 v[148:151], v96 offset:24576
	ds_read_b128 v[152:155], v96 offset:28672
	v_add_u32_e32 v96, v250, v240
	ds_read_b128 v[156:159], v96 offset:16384
	ds_read_b128 v[160:163], v96 offset:20480
	ds_read_b128 v[164:167], v96 offset:24576
	ds_read_b128 v[168:171], v96 offset:28672
	s_and_b32 s40, s39, 0x18000
	s_cmp_gt_u32 s37, 64
	s_cbranch_scc1 .LBB0_1128
	s_add_i32 s0, s40, s19
	s_add_i32 s1, s0, 0x4000
	s_mov_b32 m0, s0
	s_nop 0
	global_load_lds_dwordx4 v204, s[98:99]
	s_mov_b32 m0, s1
	s_nop 0
	global_load_lds_dwordx4 v202, s[100:101]

.LBB0_1130:
.LBB0_1131:
	v_cvt_pk_bf16_f32 v112, v210, v212
	v_cvt_pk_bf16_f32 v113, v214, v216
	v_cvt_pk_bf16_f32 v114, v220, v222
	v_cvt_pk_bf16_f32 v115, v224, v226
	v_cvt_pk_bf16_f32 v116, v211, v213
	v_cvt_pk_bf16_f32 v117, v215, v217
	v_mfma_f32_32x32x16_bf16 v[32:47], v[144:147], v[112:115], v[32:47]
	v_cvt_pk_bf16_f32 v118, v221, v223
	v_cvt_pk_bf16_f32 v119, v225, v227
	v_exp_f32_e32 v210, v97
	v_exp_f32_e32 v212, v98
	v_exp_f32_e32 v214, v99
	v_exp_f32_e32 v211, v101
	v_exp_f32_e32 v213, v102
	v_mfma_f32_32x32x16_bf16 v[16:31], v[148:151], v[112:115], v[16:31]
	v_exp_f32_e32 v215, v103
	v_cmp_neq_f32_e64 s[0:1], 0, v219
	v_mfma_f32_32x32x16_bf16 v[48:63], v[172:175], v[112:115], v[48:63]
	v_exp_f32_e32 v174, v96
	v_exp_f32_e32 v175, v100
	v_mfma_f32_32x32x16_bf16 v[0:15], v[152:155], v[112:115], v[0:15]
	v_add_u32_e32 v112, v250, v241
	v_mfma_f32_32x32x16_bf16 v[32:47], v[160:163], v[116:119], v[32:47]
	v_exp_f32_e32 v160, v104
	v_exp_f32_e32 v162, v105
	v_exp_f32_e32 v161, v108
	v_exp_f32_e32 v163, v109
	v_mfma_f32_32x32x16_bf16 v[16:31], v[164:167], v[116:119], v[16:31]
	v_exp_f32_e32 v164, v106
	v_exp_f32_e32 v166, v107
	v_exp_f32_e32 v165, v110
	v_exp_f32_e32 v167, v111
	s_nop 0
	v_pk_add_f32 v[172:173], v[164:165], v[166:167]
	v_mfma_f32_32x32x16_bf16 v[48:63], v[156:159], v[116:119], v[48:63]
	ds_read_b128 v[156:159], v112 offset:16384
	ds_read_b128 v[152:155], v112 offset:20480
	ds_read_b128 v[148:151], v112 offset:24576
	ds_read_b128 v[144:147], v112 offset:28672
	v_add_u32_e32 v112, v250, v242
	v_mfma_f32_32x32x16_bf16 v[0:15], v[168:171], v[116:119], v[0:15]
	v_add_f32_e64 v168, v174, v210
	v_add_f32_e64 v169, v175, v211
	v_add_f32_e64 v170, v212, v214
	v_add_f32_e64 v171, v213, v215
	ds_read_b128 v[124:127], v112 offset:16384
	ds_read_b128 v[120:123], v112 offset:20480
	ds_read_b128 v[116:119], v112 offset:24576
	ds_read_b128 v[112:115], v112 offset:28672
	v_pk_add_f32 v[168:169], v[168:169], v[170:171]
	v_pk_add_f32 v[170:171], v[160:161], v[162:163]
	v_pk_add_f32 v[168:169], v[168:169], v[168:169] op_sel:[0,1] op_sel_hi:[1,0]
	v_pk_add_f32 v[170:171], v[170:171], v[172:173]
	v_mov_b32_e32 v169, v177
	v_pk_add_f32 v[170:171], v[170:171], v[170:171] op_sel:[0,1] op_sel_hi:[1,0]
	s_nop 0
	v_mov_b32_e32 v171, v218
	v_pk_add_f32 v[168:169], v[168:169], v[170:171]
	s_nop 0
	v_cmp_nge_f32_e32 vcc, s97, v168
	s_or_b64 vcc, vcc, s[0:1]
	s_cbranch_vccz .LBB0_1133
	v_max_f32_e32 v64, v97, v97
	v_max_f32_e32 v65, v96, v96
	v_max_f32_e32 v64, v65, v64
	v_max_f32_e32 v65, v99, v99
	v_max_f32_e32 v66, v98, v98
	v_max_f32_e32 v65, v66, v65
	v_max_f32_e32 v66, v103, v103
	v_max_f32_e32 v67, v102, v102
	v_max_f32_e32 v66, v67, v66
	v_max3_f32 v66, v100, v101, v66
	v_max3_f32 v64, v64, v65, v66
	v_max_f32_e32 v65, v107, v107
	v_max_f32_e32 v66, v106, v106
	v_max_f32_e32 v65, v66, v65
	v_max_f32_e32 v66, v111, v111
	v_max_f32_e32 v67, v110, v110
	v_max_f32_e32 v66, v67, v66
	v_max3_f32 v65, v104, v105, v65
	v_max3_f32 v66, v108, v109, v66
	v_max3_f32 v64, v64, v65, v66
	v_add_f32_e32 v64, v64, v219
	ds_bpermute_b32 v65, v244, v64
	s_waitcnt lgkmcnt(0)
	v_max3_f32 v64, v64, v65, 0
	v_sub_f32_e32 v67, v64, v219
	v_sub_f32_e32 v68, v96, v67
	v_exp_f32_e32 v96, v68
	v_sub_f32_e32 v68, v97, v67
	v_exp_f32_e32 v170, v68
	v_sub_f32_e32 v68, v98, v67
	v_exp_f32_e32 v98, v68
	v_sub_f32_e32 v68, v99, v67
	v_exp_f32_e32 v172, v68
	v_sub_f32_e32 v68, v100, v67
	v_exp_f32_e32 v160, v68
	v_sub_f32_e32 v68, v101, v67
	v_exp_f32_e32 v162, v68
	v_sub_f32_e32 v68, v102, v67
	v_exp_f32_e32 v164, v68
	v_sub_f32_e32 v68, v103, v67
	v_exp_f32_e32 v166, v68
	v_sub_f32_e32 v68, v104, v67
	v_exp_f32_e32 v97, v68
	v_sub_f32_e32 v68, v105, v67
	v_exp_f32_e32 v171, v68
	v_sub_f32_e32 v68, v106, v67
	v_exp_f32_e32 v99, v68
	v_sub_f32_e32 v68, v107, v67
	v_exp_f32_e32 v173, v68
	v_sub_f32_e32 v68, v108, v67
	v_exp_f32_e32 v161, v68
	v_sub_f32_e32 v68, v109, v67
	v_exp_f32_e32 v163, v68
	v_sub_f32_e32 v68, v110, v67
	v_sub_f32_e32 v67, v111, v67
	v_exp_f32_e32 v165, v68
	v_exp_f32_e32 v167, v67
	v_exp_f32_e64 v66, -v64
	v_pk_add_f32 v[68:69], v[160:161], v[162:163]
	v_add_f32_e32 v201, v201, v64
	v_pk_add_f32 v[70:71], v[164:165], v[166:167]
	v_mul_f32_e32 v65, v169, v66
	v_pk_mul_f32 v[62:63], v[62:63], v[66:67] op_sel_hi:[1,0]
	v_pk_mul_f32 v[60:61], v[60:61], v[66:67] op_sel_hi:[1,0]
	v_pk_mul_f32 v[58:59], v[58:59], v[66:67] op_sel_hi:[1,0]
	v_pk_mul_f32 v[56:57], v[56:57], v[66:67] op_sel_hi:[1,0]
	v_pk_mul_f32 v[54:55], v[54:55], v[66:67] op_sel_hi:[1,0]
	v_pk_mul_f32 v[52:53], v[52:53], v[66:67] op_sel_hi:[1,0]
	v_pk_mul_f32 v[50:51], v[50:51], v[66:67] op_sel_hi:[1,0]
	v_pk_mul_f32 v[48:49], v[48:49], v[66:67] op_sel_hi:[1,0]
	v_pk_mul_f32 v[46:47], v[46:47], v[66:67] op_sel_hi:[1,0]
	v_pk_mul_f32 v[44:45], v[44:45], v[66:67] op_sel_hi:[1,0]
	v_pk_mul_f32 v[42:43], v[42:43], v[66:67] op_sel_hi:[1,0]
	v_pk_mul_f32 v[40:41], v[40:41], v[66:67] op_sel_hi:[1,0]
	v_pk_mul_f32 v[38:39], v[38:39], v[66:67] op_sel_hi:[1,0]
	v_pk_mul_f32 v[36:37], v[36:37], v[66:67] op_sel_hi:[1,0]
	v_pk_mul_f32 v[34:35], v[34:35], v[66:67] op_sel_hi:[1,0]
	v_pk_mul_f32 v[32:33], v[32:33], v[66:67] op_sel_hi:[1,0]
	v_pk_mul_f32 v[30:31], v[30:31], v[66:67] op_sel_hi:[1,0]
	v_pk_mul_f32 v[28:29], v[28:29], v[66:67] op_sel_hi:[1,0]
	v_pk_mul_f32 v[26:27], v[26:27], v[66:67] op_sel_hi:[1,0]
	v_pk_mul_f32 v[24:25], v[24:25], v[66:67] op_sel_hi:[1,0]
	v_pk_mul_f32 v[22:23], v[22:23], v[66:67] op_sel_hi:[1,0]
	v_pk_mul_f32 v[20:21], v[20:21], v[66:67] op_sel_hi:[1,0]
	v_pk_mul_f32 v[18:19], v[18:19], v[66:67] op_sel_hi:[1,0]
	v_pk_mul_f32 v[16:17], v[16:17], v[66:67] op_sel_hi:[1,0]
	v_pk_mul_f32 v[14:15], v[14:15], v[66:67] op_sel_hi:[1,0]
	v_pk_mul_f32 v[12:13], v[12:13], v[66:67] op_sel_hi:[1,0]
	v_pk_mul_f32 v[10:11], v[10:11], v[66:67] op_sel_hi:[1,0]
	v_pk_mul_f32 v[8:9], v[8:9], v[66:67] op_sel_hi:[1,0]
	v_pk_mul_f32 v[6:7], v[6:7], v[66:67] op_sel_hi:[1,0]
	v_pk_mul_f32 v[4:5], v[4:5], v[66:67] op_sel_hi:[1,0]
	v_pk_mul_f32 v[2:3], v[2:3], v[66:67] op_sel_hi:[1,0]
	v_pk_mul_f32 v[0:1], v[0:1], v[66:67] op_sel_hi:[1,0]
	v_pk_add_f32 v[66:67], v[98:99], v[172:173]
	v_pk_add_f32 v[68:69], v[68:69], v[70:71]
	v_pk_add_f32 v[70:71], v[96:97], v[170:171]
	v_xor_b32_e32 v64, 0x80000000, v201
	v_pk_add_f32 v[66:67], v[70:71], v[66:67]
	v_mov_b32_e32 v70, v64
	v_pk_add_f32 v[66:67], v[66:67], v[68:69]
	v_mov_b32_e32 v68, v64
	v_pk_add_f32 v[168:169], v[66:67], v[66:67] op_sel:[0,1] op_sel_hi:[1,0]
	v_mov_b32_e32 v66, v64
	v_mov_b32_e32 v169, v65
	v_mov_b32_e32 v65, v64
	v_mov_b32_e32 v67, v64
	v_mov_b32_e32 v69, v64
	v_mov_b32_e32 v71, v64
	v_mov_b32_e32 v72, v64
	v_mov_b32_e32 v73, v64
	v_mov_b32_e32 v74, v64
	v_mov_b32_e32 v75, v64
	v_mov_b32_e32 v76, v64
	v_mov_b32_e32 v77, v64
	v_mov_b32_e32 v78, v64
	v_mov_b32_e32 v79, v64
	v_mov_b32_e32 v80, v64
	v_mov_b32_e32 v81, v64
	v_mov_b32_e32 v82, v64
	v_mov_b32_e32 v83, v64
	v_mov_b32_e32 v84, v64
	v_mov_b32_e32 v85, v64
	v_mov_b32_e32 v86, v64
	v_mov_b32_e32 v87, v64
	v_mov_b32_e32 v88, v64
	v_mov_b32_e32 v89, v64
	v_mov_b32_e32 v90, v64
	v_mov_b32_e32 v91, v64
	v_mov_b32_e32 v92, v64
	v_mov_b32_e32 v93, v64
	v_mov_b32_e32 v94, v64
	v_mov_b32_e32 v95, v64
	v_mov_b32_e32 v174, v96
	v_mov_b32_e32 v210, v170
	v_mov_b32_e32 v212, v98
	v_mov_b32_e32 v214, v172
	v_mov_b32_e32 v175, v160
	v_mov_b32_e32 v211, v162
	v_mov_b32_e32 v213, v164
	v_mov_b32_e32 v215, v166
	v_mov_b32_e32 v160, v97
	v_mov_b32_e32 v162, v171
	v_mov_b32_e32 v164, v99
	v_mov_b32_e32 v166, v173
.LBB0_1133:
	v_cvt_pk_bf16_f32 v96, v174, v210
	v_cvt_pk_bf16_f32 v97, v212, v214
	v_cvt_pk_bf16_f32 v98, v175, v211
	v_cvt_pk_bf16_f32 v99, v213, v215
	s_waitcnt lgkmcnt(0)
	v_mfma_f32_32x32x16_bf16 v[48:63], v[156:159], v[96:99], v[48:63]
	v_mfma_f32_32x32x16_bf16 v[32:47], v[152:155], v[96:99], v[32:47]
	v_mfma_f32_32x32x16_bf16 v[16:31], v[148:151], v[96:99], v[16:31]
	v_mfma_f32_32x32x16_bf16 v[0:15], v[144:147], v[96:99], v[0:15]
	v_cvt_pk_bf16_f32 v96, v160, v162
	v_cvt_pk_bf16_f32 v97, v164, v166
	v_cvt_pk_bf16_f32 v98, v161, v163
	v_cvt_pk_bf16_f32 v99, v165, v167
	s_nop 1
	v_mfma_f32_32x32x16_bf16 v[48:63], v[124:127], v[96:99], v[48:63]
	v_mfma_f32_32x32x16_bf16 v[32:47], v[120:123], v[96:99], v[32:47]
	v_mfma_f32_32x32x16_bf16 v[16:31], v[116:119], v[96:99], v[16:31]
	v_mfma_f32_32x32x16_bf16 v[0:15], v[112:115], v[96:99], v[0:15]
	s_waitcnt vmcnt(4)
.LBB0_1135:
.LBB0_1137:
	s_add_i32 s0, s39, 0xffff0000
	s_and_b32 s0, s0, 0x18000
	v_or_b32_e32 v104, s0, v195
	v_add_u32_e32 v96, v104, v234
	v_add_u32_e32 v97, v104, v235
	v_add_u32_e32 v105, v104, v236
	v_add_u32_e32 v108, v104, v237
	s_waitcnt lgkmcnt(0)
	s_barrier
	ds_read_b128 v[100:103], v96
	ds_read_b128 v[96:99], v97
	ds_read_b128 v[104:107], v105
	ds_read_b128 v[108:111], v108
	s_cmp_gt_u32 s37, 64
	s_cbranch_scc1 .LBB0_1125
	s_add_i32 s8, s40, s19
	v_add_u32_e32 v112, 0x20000, v204
	s_add_i32 m0, s8, 0x2000
	s_addk_i32 s8, 0x6000
	v_add_u32_e32 v114, 0x88000, v202
	global_load_lds_dwordx4 v112, s[98:99]
	s_mov_b32 m0, s8
	s_nop 0
	global_load_lds_dwordx4 v114, s[100:101]
	s_branch .LBB0_1125

	.amdhsa_kernel _Z14fwd_megakernel6Params
		.amdhsa_group_segment_fixed_size 147472
		.amdhsa_private_segment_fixed_size 0
		.amdhsa_kernarg_size 432
		.amdhsa_user_sgpr_count 2
		.amdhsa_user_sgpr_dispatch_ptr 0
		.amdhsa_user_sgpr_queue_ptr 0
		.amdhsa_user_sgpr_kernarg_segment_ptr 1
		.amdhsa_user_sgpr_dispatch_id 0
		.amdhsa_user_sgpr_kernarg_preload_length 0
		.amdhsa_user_sgpr_kernarg_preload_offset 0
		.amdhsa_user_sgpr_private_segment_size 0
		.amdhsa_uses_dynamic_stack 0
		.amdhsa_enable_private_segment 0
		.amdhsa_system_sgpr_workgroup_id_x 1
		.amdhsa_system_sgpr_workgroup_id_y 0
		.amdhsa_system_sgpr_workgroup_id_z 0
		.amdhsa_system_sgpr_workgroup_info 0
		.amdhsa_system_vgpr_workitem_id 2
		.amdhsa_next_free_vgpr 254
		.amdhsa_next_free_sgpr 102
		.amdhsa_accum_offset 256
		.amdhsa_reserve_vcc 1
		.amdhsa_float_round_mode_32 0
		.amdhsa_float_round_mode_16_64 0
		.amdhsa_float_denorm_mode_32 3
		.amdhsa_float_denorm_mode_16_64 3
		.amdhsa_dx10_clamp 1
		.amdhsa_ieee_mode 1
		.amdhsa_fp16_overflow 0
		.amdhsa_tg_split 0
		.amdhsa_exception_fp_ieee_invalid_op 0
		.amdhsa_exception_fp_denorm_src 0
		.amdhsa_exception_fp_ieee_div_zero 0
		.amdhsa_exception_fp_ieee_overflow 0
		.amdhsa_exception_fp_ieee_underflow 0
		.amdhsa_exception_fp_ieee_inexact 0
		.amdhsa_exception_int_div_zero 0
	.end_amdhsa_kernel

amdhsa.kernels:
  - .agpr_count:     0
    .args:
      - .offset:         0
        .size:           176
        .value_kind:     by_value
      - .offset:         176
        .size:           4
        .value_kind:     hidden_block_count_x
      - .offset:         180
        .size:           4
        .value_kind:     hidden_block_count_y
      - .offset:         184
        .size:           4
        .value_kind:     hidden_block_count_z
      - .offset:         188
        .size:           2
        .value_kind:     hidden_group_size_x
      - .offset:         190
        .size:           2
        .value_kind:     hidden_group_size_y
      - .offset:         192
        .size:           2
        .value_kind:     hidden_group_size_z
      - .offset:         194
        .size:           2
        .value_kind:     hidden_remainder_x
      - .offset:         196
        .size:           2
        .value_kind:     hidden_remainder_y
      - .offset:         198
        .size:           2
        .value_kind:     hidden_remainder_z
      - .offset:         216
        .size:           8
        .value_kind:     hidden_global_offset_x
      - .offset:         224
        .size:           8
        .value_kind:     hidden_global_offset_y
      - .offset:         232
        .size:           8
        .value_kind:     hidden_global_offset_z
      - .offset:         240
        .size:           2
        .value_kind:     hidden_grid_dims
      - .offset:         264
        .size:           8
        .value_kind:     hidden_multigrid_sync_arg
    .group_segment_fixed_size: 147472
    .kernarg_segment_align: 8
    .kernarg_segment_size: 432
    .language:       OpenCL C
    .language_version:
      - 2
      - 0
    .max_flat_workgroup_size: 512
    .name:           _Z14fwd_megakernel6Params
    .private_segment_fixed_size: 0
    .sgpr_count:     108
    .sgpr_spill_count: 191
    .symbol:         _Z14fwd_megakernel6Params.kd
    .uniform_work_group_size: 1
    .uses_dynamic_stack: false
    .vgpr_count:     254
    .vgpr_spill_count: 0
    .wavefront_size: 64
